# prologue adaLN mat-vec: 64 weight loads in flight per batch (2 round trips instead of 4)
# speedup vs baseline: 1.0004x; 1.0004x over previous
; DI int tidx() { int t = __builtin_amdgcn_workitem_id_x(); asm volatile("" : "+v"(t)); return t; }
; DI void phase_prologue_a(char* lds, const Params& p, int bid, int nb) {
;     ...
;       const int j = jb * 512 + tidx();
;       float a0 = 0.f, a1 = 0.f, a2 = 0.f, a3 = 0.f, a4 = 0.f, a5 = 0.f, a6 = 0.f, a7 = 0.f;
;       const float* w = p.w_ada + ((size_t)l * 1024 + kc * 128) * 6144 + j;
; #pragma unroll 4
;       for (int k = 0; k < 128; ++k) { const float wv = w[(size_t)k * 6144];
;         a0 += sl[k] * wv; a1 += sl[128 + k] * wv; a2 += sl[256 + k] * wv; a3 += sl[384 + k] * wv; a4 += sl[512 + k] * wv; a5 += sl[640 + k] * wv; a6 += sl[768 + k] * wv; a7 += sl[896 + k] * wv; }
.Lada_batch:
	v_lshl_add_u64 v[92:93], v[58:59], 0, s[4:5]
	global_load_dword v128, v[92:93], off
	s_add_u32 s4, s4, 0x6000
	s_addc_u32 s5, s5, 0
	v_lshl_add_u64 v[94:95], v[58:59], 0, s[4:5]
	global_load_dword v129, v[94:95], off
	s_add_u32 s4, s4, 0x6000
	s_addc_u32 s5, s5, 0
	v_lshl_add_u64 v[92:93], v[58:59], 0, s[4:5]
	global_load_dword v130, v[92:93], off
	s_add_u32 s4, s4, 0x6000
	s_addc_u32 s5, s5, 0
	v_lshl_add_u64 v[94:95], v[58:59], 0, s[4:5]
	global_load_dword v131, v[94:95], off
	s_add_u32 s4, s4, 0x6000
	s_addc_u32 s5, s5, 0
	v_lshl_add_u64 v[92:93], v[58:59], 0, s[4:5]
	global_load_dword v132, v[92:93], off
	s_add_u32 s4, s4, 0x6000
	s_addc_u32 s5, s5, 0
	v_lshl_add_u64 v[94:95], v[58:59], 0, s[4:5]
	global_load_dword v133, v[94:95], off
	s_add_u32 s4, s4, 0x6000
	s_addc_u32 s5, s5, 0
	v_lshl_add_u64 v[92:93], v[58:59], 0, s[4:5]
	global_load_dword v134, v[92:93], off
	s_add_u32 s4, s4, 0x6000
	s_addc_u32 s5, s5, 0
	v_lshl_add_u64 v[94:95], v[58:59], 0, s[4:5]
	global_load_dword v135, v[94:95], off
	s_add_u32 s4, s4, 0x6000
	s_addc_u32 s5, s5, 0
	v_lshl_add_u64 v[92:93], v[58:59], 0, s[4:5]
	global_load_dword v136, v[92:93], off
	s_add_u32 s4, s4, 0x6000
	s_addc_u32 s5, s5, 0
	v_lshl_add_u64 v[94:95], v[58:59], 0, s[4:5]
	global_load_dword v137, v[94:95], off
	s_add_u32 s4, s4, 0x6000
	s_addc_u32 s5, s5, 0
	v_lshl_add_u64 v[92:93], v[58:59], 0, s[4:5]
	global_load_dword v138, v[92:93], off
	s_add_u32 s4, s4, 0x6000
	s_addc_u32 s5, s5, 0
	v_lshl_add_u64 v[94:95], v[58:59], 0, s[4:5]
	global_load_dword v139, v[94:95], off
	s_add_u32 s4, s4, 0x6000
	s_addc_u32 s5, s5, 0
	v_lshl_add_u64 v[92:93], v[58:59], 0, s[4:5]
	global_load_dword v140, v[92:93], off
	s_add_u32 s4, s4, 0x6000
	s_addc_u32 s5, s5, 0
	v_lshl_add_u64 v[94:95], v[58:59], 0, s[4:5]
	global_load_dword v141, v[94:95], off
	s_add_u32 s4, s4, 0x6000
	s_addc_u32 s5, s5, 0
	v_lshl_add_u64 v[92:93], v[58:59], 0, s[4:5]
	global_load_dword v142, v[92:93], off
	s_add_u32 s4, s4, 0x6000
	s_addc_u32 s5, s5, 0
	v_lshl_add_u64 v[94:95], v[58:59], 0, s[4:5]
	global_load_dword v143, v[94:95], off
	s_add_u32 s4, s4, 0x6000
	s_addc_u32 s5, s5, 0
	v_lshl_add_u64 v[92:93], v[58:59], 0, s[4:5]
	global_load_dword v144, v[92:93], off
	s_add_u32 s4, s4, 0x6000
	s_addc_u32 s5, s5, 0
	v_lshl_add_u64 v[94:95], v[58:59], 0, s[4:5]
	global_load_dword v145, v[94:95], off
	s_add_u32 s4, s4, 0x6000
	s_addc_u32 s5, s5, 0
	v_lshl_add_u64 v[92:93], v[58:59], 0, s[4:5]
	global_load_dword v146, v[92:93], off
	s_add_u32 s4, s4, 0x6000
	s_addc_u32 s5, s5, 0
	v_lshl_add_u64 v[94:95], v[58:59], 0, s[4:5]
	global_load_dword v147, v[94:95], off
	s_add_u32 s4, s4, 0x6000
	s_addc_u32 s5, s5, 0
	v_lshl_add_u64 v[92:93], v[58:59], 0, s[4:5]
	global_load_dword v148, v[92:93], off
	s_add_u32 s4, s4, 0x6000
	s_addc_u32 s5, s5, 0
	v_lshl_add_u64 v[94:95], v[58:59], 0, s[4:5]
	global_load_dword v149, v[94:95], off
	s_add_u32 s4, s4, 0x6000
	s_addc_u32 s5, s5, 0
	v_lshl_add_u64 v[92:93], v[58:59], 0, s[4:5]
	global_load_dword v150, v[92:93], off
	s_add_u32 s4, s4, 0x6000
	s_addc_u32 s5, s5, 0
	v_lshl_add_u64 v[94:95], v[58:59], 0, s[4:5]
	global_load_dword v151, v[94:95], off
	s_add_u32 s4, s4, 0x6000
	s_addc_u32 s5, s5, 0
	v_lshl_add_u64 v[92:93], v[58:59], 0, s[4:5]
	global_load_dword v152, v[92:93], off
	s_add_u32 s4, s4, 0x6000
	s_addc_u32 s5, s5, 0
	v_lshl_add_u64 v[94:95], v[58:59], 0, s[4:5]
	global_load_dword v153, v[94:95], off
	s_add_u32 s4, s4, 0x6000
	s_addc_u32 s5, s5, 0
	v_lshl_add_u64 v[92:93], v[58:59], 0, s[4:5]
	global_load_dword v154, v[92:93], off
	s_add_u32 s4, s4, 0x6000
	s_addc_u32 s5, s5, 0
	v_lshl_add_u64 v[94:95], v[58:59], 0, s[4:5]
	global_load_dword v155, v[94:95], off
	s_add_u32 s4, s4, 0x6000
	s_addc_u32 s5, s5, 0
	v_lshl_add_u64 v[92:93], v[58:59], 0, s[4:5]
	global_load_dword v156, v[92:93], off
	s_add_u32 s4, s4, 0x6000
	s_addc_u32 s5, s5, 0
	v_lshl_add_u64 v[94:95], v[58:59], 0, s[4:5]
	global_load_dword v157, v[94:95], off
	s_add_u32 s4, s4, 0x6000
	s_addc_u32 s5, s5, 0
	v_lshl_add_u64 v[92:93], v[58:59], 0, s[4:5]
	global_load_dword v158, v[92:93], off
	s_add_u32 s4, s4, 0x6000
	s_addc_u32 s5, s5, 0
	v_lshl_add_u64 v[94:95], v[58:59], 0, s[4:5]
	global_load_dword v159, v[94:95], off
	s_add_u32 s4, s4, 0x6000
	s_addc_u32 s5, s5, 0
	v_lshl_add_u64 v[92:93], v[58:59], 0, s[4:5]
	global_load_dword v160, v[92:93], off
	s_add_u32 s4, s4, 0x6000
	s_addc_u32 s5, s5, 0
	v_lshl_add_u64 v[94:95], v[58:59], 0, s[4:5]
	global_load_dword v161, v[94:95], off
	s_add_u32 s4, s4, 0x6000
	s_addc_u32 s5, s5, 0
	v_lshl_add_u64 v[92:93], v[58:59], 0, s[4:5]
	global_load_dword v162, v[92:93], off
	s_add_u32 s4, s4, 0x6000
	s_addc_u32 s5, s5, 0
	v_lshl_add_u64 v[94:95], v[58:59], 0, s[4:5]
	global_load_dword v163, v[94:95], off
	s_add_u32 s4, s4, 0x6000
	s_addc_u32 s5, s5, 0
	v_lshl_add_u64 v[92:93], v[58:59], 0, s[4:5]
	global_load_dword v164, v[92:93], off
	s_add_u32 s4, s4, 0x6000
	s_addc_u32 s5, s5, 0
	v_lshl_add_u64 v[94:95], v[58:59], 0, s[4:5]
	global_load_dword v165, v[94:95], off
	s_add_u32 s4, s4, 0x6000
	s_addc_u32 s5, s5, 0
	v_lshl_add_u64 v[92:93], v[58:59], 0, s[4:5]
	global_load_dword v166, v[92:93], off
	s_add_u32 s4, s4, 0x6000
	s_addc_u32 s5, s5, 0
	v_lshl_add_u64 v[94:95], v[58:59], 0, s[4:5]
	global_load_dword v167, v[94:95], off
	s_add_u32 s4, s4, 0x6000
	s_addc_u32 s5, s5, 0
	v_lshl_add_u64 v[92:93], v[58:59], 0, s[4:5]
	global_load_dword v168, v[92:93], off
	s_add_u32 s4, s4, 0x6000
	s_addc_u32 s5, s5, 0
	v_lshl_add_u64 v[94:95], v[58:59], 0, s[4:5]
	global_load_dword v169, v[94:95], off
	s_add_u32 s4, s4, 0x6000
	s_addc_u32 s5, s5, 0
	v_lshl_add_u64 v[92:93], v[58:59], 0, s[4:5]
; DI void phase_prologue_a(char* lds, const Params& p, int bid, int nb) {
;     ...
; #pragma unroll 4
;       for (int k = 0; k < 128; ++k) { const float wv = w[(size_t)k * 6144];
;         a0 += sl[k] * wv; a1 += sl[128 + k] * wv; a2 += sl[256 + k] * wv; a3 += sl[384 + k] * wv; a4 += sl[512 + k] * wv; a5 += sl[640 + k] * wv; a6 += sl[768 + k] * wv; a7 += sl[896 + k] * wv; }
	global_load_dword v170, v[92:93], off
	s_add_u32 s4, s4, 0x6000
	s_addc_u32 s5, s5, 0
	v_lshl_add_u64 v[94:95], v[58:59], 0, s[4:5]
	global_load_dword v171, v[94:95], off
	s_add_u32 s4, s4, 0x6000
	s_addc_u32 s5, s5, 0
	v_lshl_add_u64 v[92:93], v[58:59], 0, s[4:5]
	global_load_dword v172, v[92:93], off
	s_add_u32 s4, s4, 0x6000
	s_addc_u32 s5, s5, 0
	v_lshl_add_u64 v[94:95], v[58:59], 0, s[4:5]
	global_load_dword v173, v[94:95], off
	s_add_u32 s4, s4, 0x6000
	s_addc_u32 s5, s5, 0
	v_lshl_add_u64 v[92:93], v[58:59], 0, s[4:5]
	global_load_dword v174, v[92:93], off
	s_add_u32 s4, s4, 0x6000
	s_addc_u32 s5, s5, 0
	v_lshl_add_u64 v[94:95], v[58:59], 0, s[4:5]
	global_load_dword v175, v[94:95], off
	s_add_u32 s4, s4, 0x6000
	s_addc_u32 s5, s5, 0
	v_lshl_add_u64 v[92:93], v[58:59], 0, s[4:5]
	global_load_dword v176, v[92:93], off
	s_add_u32 s4, s4, 0x6000
	s_addc_u32 s5, s5, 0
	v_lshl_add_u64 v[94:95], v[58:59], 0, s[4:5]
	global_load_dword v177, v[94:95], off
	s_add_u32 s4, s4, 0x6000
	s_addc_u32 s5, s5, 0
	v_lshl_add_u64 v[92:93], v[58:59], 0, s[4:5]
	global_load_dword v178, v[92:93], off
	s_add_u32 s4, s4, 0x6000
	s_addc_u32 s5, s5, 0
	v_lshl_add_u64 v[94:95], v[58:59], 0, s[4:5]
	global_load_dword v179, v[94:95], off
	s_add_u32 s4, s4, 0x6000
	s_addc_u32 s5, s5, 0
	v_lshl_add_u64 v[92:93], v[58:59], 0, s[4:5]
	global_load_dword v180, v[92:93], off
	s_add_u32 s4, s4, 0x6000
	s_addc_u32 s5, s5, 0
	v_lshl_add_u64 v[94:95], v[58:59], 0, s[4:5]
	global_load_dword v181, v[94:95], off
	s_add_u32 s4, s4, 0x6000
	s_addc_u32 s5, s5, 0
	v_lshl_add_u64 v[92:93], v[58:59], 0, s[4:5]
	global_load_dword v182, v[92:93], off
	s_add_u32 s4, s4, 0x6000
	s_addc_u32 s5, s5, 0
	v_lshl_add_u64 v[94:95], v[58:59], 0, s[4:5]
	global_load_dword v183, v[94:95], off
	s_add_u32 s4, s4, 0x6000
	s_addc_u32 s5, s5, 0
	v_lshl_add_u64 v[92:93], v[58:59], 0, s[4:5]
	global_load_dword v184, v[92:93], off
	s_add_u32 s4, s4, 0x6000
	s_addc_u32 s5, s5, 0
	v_lshl_add_u64 v[94:95], v[58:59], 0, s[4:5]
	global_load_dword v185, v[94:95], off
	s_add_u32 s4, s4, 0x6000
	s_addc_u32 s5, s5, 0
	v_lshl_add_u64 v[92:93], v[58:59], 0, s[4:5]
	global_load_dword v186, v[92:93], off
	s_add_u32 s4, s4, 0x6000
	s_addc_u32 s5, s5, 0
	v_lshl_add_u64 v[94:95], v[58:59], 0, s[4:5]
	global_load_dword v187, v[94:95], off
	s_add_u32 s4, s4, 0x6000
	s_addc_u32 s5, s5, 0
	v_lshl_add_u64 v[92:93], v[58:59], 0, s[4:5]
	global_load_dword v188, v[92:93], off
	s_add_u32 s4, s4, 0x6000
	s_addc_u32 s5, s5, 0
	v_lshl_add_u64 v[94:95], v[58:59], 0, s[4:5]
	global_load_dword v189, v[94:95], off
	s_add_u32 s4, s4, 0x6000
	s_addc_u32 s5, s5, 0
	v_lshl_add_u64 v[92:93], v[58:59], 0, s[4:5]
	global_load_dword v190, v[92:93], off
	s_add_u32 s4, s4, 0x6000
	s_addc_u32 s5, s5, 0
	v_lshl_add_u64 v[94:95], v[58:59], 0, s[4:5]
	global_load_dword v191, v[94:95], off
	s_add_u32 s4, s4, 0x6000
	s_addc_u32 s5, s5, 0
	v_mov_b32_e32 v90, s46
	ds_read_b128 v[96:99], v90
	ds_read_b128 v[100:103], v90 offset:512
	ds_read_b128 v[104:107], v90 offset:1024
	ds_read_b128 v[108:111], v90 offset:1536
	ds_read_b128 v[112:115], v90 offset:2048
	ds_read_b128 v[116:119], v90 offset:2560
	ds_read_b128 v[120:123], v90 offset:3072
	ds_read_b128 v[124:127], v90 offset:3584
	s_add_i32 s46, s46, 16
	v_mov_b32_e32 v90, s46
	ds_read_b128 v[208:211], v90
	ds_read_b128 v[212:215], v90 offset:512
	ds_read_b128 v[216:219], v90 offset:1024
	ds_read_b128 v[220:223], v90 offset:1536
	ds_read_b128 v[224:227], v90 offset:2048
	ds_read_b128 v[228:231], v90 offset:2560
	ds_read_b128 v[232:235], v90 offset:3072
	ds_read_b128 v[236:239], v90 offset:3584
	s_add_i32 s46, s46, 16
	s_waitcnt lgkmcnt(8)
	s_waitcnt vmcnt(60)
	v_fma_f32 v10, v128, v96, v10
	v_fma_f32 v11, v128, v100, v11
	v_fma_f32 v18, v128, v104, v18
	v_fma_f32 v19, v128, v108, v19
	v_fma_f32 v26, v128, v112, v26
	v_fma_f32 v27, v128, v116, v27
	v_fma_f32 v60, v128, v120, v60
	v_fma_f32 v61, v128, v124, v61
	v_fma_f32 v10, v129, v97, v10
	v_fma_f32 v11, v129, v101, v11
	v_fma_f32 v18, v129, v105, v18
	v_fma_f32 v19, v129, v109, v19
	v_fma_f32 v26, v129, v113, v26
	v_fma_f32 v27, v129, v117, v27
	v_fma_f32 v60, v129, v121, v60
	v_fma_f32 v61, v129, v125, v61
	v_fma_f32 v10, v130, v98, v10
	v_fma_f32 v11, v130, v102, v11
	v_fma_f32 v18, v130, v106, v18
	v_fma_f32 v19, v130, v110, v19
	v_fma_f32 v26, v130, v114, v26
	v_fma_f32 v27, v130, v118, v27
	v_fma_f32 v60, v130, v122, v60
	v_fma_f32 v61, v130, v126, v61
	v_fma_f32 v10, v131, v99, v10
	v_fma_f32 v11, v131, v103, v11
	v_fma_f32 v18, v131, v107, v18
	v_fma_f32 v19, v131, v111, v19
	v_fma_f32 v26, v131, v115, v26
	v_fma_f32 v27, v131, v119, v27
	v_fma_f32 v60, v131, v123, v60
	v_fma_f32 v61, v131, v127, v61
	v_mov_b32_e32 v90, s46
	ds_read_b128 v[96:99], v90
	ds_read_b128 v[100:103], v90 offset:512
	ds_read_b128 v[104:107], v90 offset:1024
	ds_read_b128 v[108:111], v90 offset:1536
	ds_read_b128 v[112:115], v90 offset:2048
	ds_read_b128 v[116:119], v90 offset:2560
	ds_read_b128 v[120:123], v90 offset:3072
	ds_read_b128 v[124:127], v90 offset:3584
	s_add_i32 s46, s46, 16
	s_waitcnt lgkmcnt(8)
	s_waitcnt vmcnt(56)
; DI void phase_prologue_a(char* lds, const Params& p, int bid, int nb) {
;     ...
; #pragma unroll 4
;       for (int k = 0; k < 128; ++k) { const float wv = w[(size_t)k * 6144];
;         a0 += sl[k] * wv; a1 += sl[128 + k] * wv; a2 += sl[256 + k] * wv; a3 += sl[384 + k] * wv; a4 += sl[512 + k] * wv; a5 += sl[640 + k] * wv; a6 += sl[768 + k] * wv; a7 += sl[896 + k] * wv; }
	v_fma_f32 v10, v132, v208, v10
	v_fma_f32 v11, v132, v212, v11
	v_fma_f32 v18, v132, v216, v18
	v_fma_f32 v19, v132, v220, v19
	v_fma_f32 v26, v132, v224, v26
	v_fma_f32 v27, v132, v228, v27
	v_fma_f32 v60, v132, v232, v60
	v_fma_f32 v61, v132, v236, v61
	v_fma_f32 v10, v133, v209, v10
	v_fma_f32 v11, v133, v213, v11
	v_fma_f32 v18, v133, v217, v18
	v_fma_f32 v19, v133, v221, v19
	v_fma_f32 v26, v133, v225, v26
	v_fma_f32 v27, v133, v229, v27
	v_fma_f32 v60, v133, v233, v60
	v_fma_f32 v61, v133, v237, v61
	v_fma_f32 v10, v134, v210, v10
	v_fma_f32 v11, v134, v214, v11
	v_fma_f32 v18, v134, v218, v18
	v_fma_f32 v19, v134, v222, v19
	v_fma_f32 v26, v134, v226, v26
	v_fma_f32 v27, v134, v230, v27
	v_fma_f32 v60, v134, v234, v60
	v_fma_f32 v61, v134, v238, v61
	v_fma_f32 v10, v135, v211, v10
	v_fma_f32 v11, v135, v215, v11
	v_fma_f32 v18, v135, v219, v18
	v_fma_f32 v19, v135, v223, v19
	v_fma_f32 v26, v135, v227, v26
	v_fma_f32 v27, v135, v231, v27
	v_fma_f32 v60, v135, v235, v60
	v_fma_f32 v61, v135, v239, v61
	v_mov_b32_e32 v90, s46
	ds_read_b128 v[208:211], v90
	ds_read_b128 v[212:215], v90 offset:512
	ds_read_b128 v[216:219], v90 offset:1024
	ds_read_b128 v[220:223], v90 offset:1536
	ds_read_b128 v[224:227], v90 offset:2048
	ds_read_b128 v[228:231], v90 offset:2560
	ds_read_b128 v[232:235], v90 offset:3072
	ds_read_b128 v[236:239], v90 offset:3584
	s_add_i32 s46, s46, 16
	s_waitcnt lgkmcnt(8)
	s_waitcnt vmcnt(52)
	v_fma_f32 v10, v136, v96, v10
	v_fma_f32 v11, v136, v100, v11
	v_fma_f32 v18, v136, v104, v18
	v_fma_f32 v19, v136, v108, v19
	v_fma_f32 v26, v136, v112, v26
	v_fma_f32 v27, v136, v116, v27
	v_fma_f32 v60, v136, v120, v60
	v_fma_f32 v61, v136, v124, v61
	v_fma_f32 v10, v137, v97, v10
	v_fma_f32 v11, v137, v101, v11
	v_fma_f32 v18, v137, v105, v18
	v_fma_f32 v19, v137, v109, v19
	v_fma_f32 v26, v137, v113, v26
	v_fma_f32 v27, v137, v117, v27
	v_fma_f32 v60, v137, v121, v60
	v_fma_f32 v61, v137, v125, v61
	v_fma_f32 v10, v138, v98, v10
	v_fma_f32 v11, v138, v102, v11
	v_fma_f32 v18, v138, v106, v18
	v_fma_f32 v19, v138, v110, v19
	v_fma_f32 v26, v138, v114, v26
	v_fma_f32 v27, v138, v118, v27
	v_fma_f32 v60, v138, v122, v60
	v_fma_f32 v61, v138, v126, v61
	v_fma_f32 v10, v139, v99, v10
	v_fma_f32 v11, v139, v103, v11
	v_fma_f32 v18, v139, v107, v18
	v_fma_f32 v19, v139, v111, v19
	v_fma_f32 v26, v139, v115, v26
	v_fma_f32 v27, v139, v119, v27
	v_fma_f32 v60, v139, v123, v60
	v_fma_f32 v61, v139, v127, v61
	v_mov_b32_e32 v90, s46
	ds_read_b128 v[96:99], v90
	ds_read_b128 v[100:103], v90 offset:512
	ds_read_b128 v[104:107], v90 offset:1024
	ds_read_b128 v[108:111], v90 offset:1536
	ds_read_b128 v[112:115], v90 offset:2048
	ds_read_b128 v[116:119], v90 offset:2560
	ds_read_b128 v[120:123], v90 offset:3072
	ds_read_b128 v[124:127], v90 offset:3584
	s_add_i32 s46, s46, 16
	s_waitcnt lgkmcnt(8)
	s_waitcnt vmcnt(48)
	v_fma_f32 v10, v140, v208, v10
	v_fma_f32 v11, v140, v212, v11
	v_fma_f32 v18, v140, v216, v18
	v_fma_f32 v19, v140, v220, v19
	v_fma_f32 v26, v140, v224, v26
	v_fma_f32 v27, v140, v228, v27
	v_fma_f32 v60, v140, v232, v60
	v_fma_f32 v61, v140, v236, v61
	v_fma_f32 v10, v141, v209, v10
	v_fma_f32 v11, v141, v213, v11
	v_fma_f32 v18, v141, v217, v18
	v_fma_f32 v19, v141, v221, v19
	v_fma_f32 v26, v141, v225, v26
	v_fma_f32 v27, v141, v229, v27
	v_fma_f32 v60, v141, v233, v60
	v_fma_f32 v61, v141, v237, v61
	v_fma_f32 v10, v142, v210, v10
	v_fma_f32 v11, v142, v214, v11
	v_fma_f32 v18, v142, v218, v18
	v_fma_f32 v19, v142, v222, v19
	v_fma_f32 v26, v142, v226, v26
	v_fma_f32 v27, v142, v230, v27
	v_fma_f32 v60, v142, v234, v60
	v_fma_f32 v61, v142, v238, v61
	v_fma_f32 v10, v143, v211, v10
	v_fma_f32 v11, v143, v215, v11
	v_fma_f32 v18, v143, v219, v18
	v_fma_f32 v19, v143, v223, v19
	v_fma_f32 v26, v143, v227, v26
	v_fma_f32 v27, v143, v231, v27
	v_fma_f32 v60, v143, v235, v60
	v_fma_f32 v61, v143, v239, v61
	v_mov_b32_e32 v90, s46
	ds_read_b128 v[208:211], v90
	ds_read_b128 v[212:215], v90 offset:512
	ds_read_b128 v[216:219], v90 offset:1024
	ds_read_b128 v[220:223], v90 offset:1536
	ds_read_b128 v[224:227], v90 offset:2048
	ds_read_b128 v[228:231], v90 offset:2560
	ds_read_b128 v[232:235], v90 offset:3072
	ds_read_b128 v[236:239], v90 offset:3584
	s_add_i32 s46, s46, 16
	s_waitcnt lgkmcnt(8)
	s_waitcnt vmcnt(44)
	v_fma_f32 v10, v144, v96, v10
	v_fma_f32 v11, v144, v100, v11
	v_fma_f32 v18, v144, v104, v18
	v_fma_f32 v19, v144, v108, v19
	v_fma_f32 v26, v144, v112, v26
	v_fma_f32 v27, v144, v116, v27
	v_fma_f32 v60, v144, v120, v60
	v_fma_f32 v61, v144, v124, v61
	v_fma_f32 v10, v145, v97, v10
	v_fma_f32 v11, v145, v101, v11
	v_fma_f32 v18, v145, v105, v18
	v_fma_f32 v19, v145, v109, v19
	v_fma_f32 v26, v145, v113, v26
	v_fma_f32 v27, v145, v117, v27
	v_fma_f32 v60, v145, v121, v60
	v_fma_f32 v61, v145, v125, v61
	v_fma_f32 v10, v146, v98, v10
	v_fma_f32 v11, v146, v102, v11
	v_fma_f32 v18, v146, v106, v18
	v_fma_f32 v19, v146, v110, v19
	v_fma_f32 v26, v146, v114, v26
	v_fma_f32 v27, v146, v118, v27
	v_fma_f32 v60, v146, v122, v60
	v_fma_f32 v61, v146, v126, v61
	v_fma_f32 v10, v147, v99, v10
	v_fma_f32 v11, v147, v103, v11
	v_fma_f32 v18, v147, v107, v18
	v_fma_f32 v19, v147, v111, v19
	v_fma_f32 v26, v147, v115, v26
	v_fma_f32 v27, v147, v119, v27
	v_fma_f32 v60, v147, v123, v60
	v_fma_f32 v61, v147, v127, v61
	v_mov_b32_e32 v90, s46
	ds_read_b128 v[96:99], v90
	ds_read_b128 v[100:103], v90 offset:512
	ds_read_b128 v[104:107], v90 offset:1024
	ds_read_b128 v[108:111], v90 offset:1536
	ds_read_b128 v[112:115], v90 offset:2048
	ds_read_b128 v[116:119], v90 offset:2560
	ds_read_b128 v[120:123], v90 offset:3072
	ds_read_b128 v[124:127], v90 offset:3584
	s_add_i32 s46, s46, 16
	s_waitcnt lgkmcnt(8)
; DI void phase_prologue_a(char* lds, const Params& p, int bid, int nb) {
;     ...
; #pragma unroll 4
;       for (int k = 0; k < 128; ++k) { const float wv = w[(size_t)k * 6144];
;         a0 += sl[k] * wv; a1 += sl[128 + k] * wv; a2 += sl[256 + k] * wv; a3 += sl[384 + k] * wv; a4 += sl[512 + k] * wv; a5 += sl[640 + k] * wv; a6 += sl[768 + k] * wv; a7 += sl[896 + k] * wv; }
	s_waitcnt vmcnt(40)
	v_fma_f32 v10, v148, v208, v10
	v_fma_f32 v11, v148, v212, v11
	v_fma_f32 v18, v148, v216, v18
	v_fma_f32 v19, v148, v220, v19
	v_fma_f32 v26, v148, v224, v26
	v_fma_f32 v27, v148, v228, v27
	v_fma_f32 v60, v148, v232, v60
	v_fma_f32 v61, v148, v236, v61
	v_fma_f32 v10, v149, v209, v10
	v_fma_f32 v11, v149, v213, v11
	v_fma_f32 v18, v149, v217, v18
	v_fma_f32 v19, v149, v221, v19
	v_fma_f32 v26, v149, v225, v26
	v_fma_f32 v27, v149, v229, v27
	v_fma_f32 v60, v149, v233, v60
	v_fma_f32 v61, v149, v237, v61
	v_fma_f32 v10, v150, v210, v10
	v_fma_f32 v11, v150, v214, v11
	v_fma_f32 v18, v150, v218, v18
	v_fma_f32 v19, v150, v222, v19
	v_fma_f32 v26, v150, v226, v26
	v_fma_f32 v27, v150, v230, v27
	v_fma_f32 v60, v150, v234, v60
	v_fma_f32 v61, v150, v238, v61
	v_fma_f32 v10, v151, v211, v10
	v_fma_f32 v11, v151, v215, v11
	v_fma_f32 v18, v151, v219, v18
	v_fma_f32 v19, v151, v223, v19
	v_fma_f32 v26, v151, v227, v26
	v_fma_f32 v27, v151, v231, v27
	v_fma_f32 v60, v151, v235, v60
	v_fma_f32 v61, v151, v239, v61
	v_mov_b32_e32 v90, s46
	ds_read_b128 v[208:211], v90
	ds_read_b128 v[212:215], v90 offset:512
	ds_read_b128 v[216:219], v90 offset:1024
	ds_read_b128 v[220:223], v90 offset:1536
	ds_read_b128 v[224:227], v90 offset:2048
	ds_read_b128 v[228:231], v90 offset:2560
	ds_read_b128 v[232:235], v90 offset:3072
	ds_read_b128 v[236:239], v90 offset:3584
	s_add_i32 s46, s46, 16
	s_waitcnt lgkmcnt(8)
	s_waitcnt vmcnt(36)
	v_fma_f32 v10, v152, v96, v10
	v_fma_f32 v11, v152, v100, v11
	v_fma_f32 v18, v152, v104, v18
	v_fma_f32 v19, v152, v108, v19
	v_fma_f32 v26, v152, v112, v26
	v_fma_f32 v27, v152, v116, v27
	v_fma_f32 v60, v152, v120, v60
	v_fma_f32 v61, v152, v124, v61
	v_fma_f32 v10, v153, v97, v10
	v_fma_f32 v11, v153, v101, v11
	v_fma_f32 v18, v153, v105, v18
	v_fma_f32 v19, v153, v109, v19
	v_fma_f32 v26, v153, v113, v26
	v_fma_f32 v27, v153, v117, v27
	v_fma_f32 v60, v153, v121, v60
	v_fma_f32 v61, v153, v125, v61
	v_fma_f32 v10, v154, v98, v10
	v_fma_f32 v11, v154, v102, v11
	v_fma_f32 v18, v154, v106, v18
	v_fma_f32 v19, v154, v110, v19
	v_fma_f32 v26, v154, v114, v26
	v_fma_f32 v27, v154, v118, v27
	v_fma_f32 v60, v154, v122, v60
	v_fma_f32 v61, v154, v126, v61
	v_fma_f32 v10, v155, v99, v10
	v_fma_f32 v11, v155, v103, v11
	v_fma_f32 v18, v155, v107, v18
	v_fma_f32 v19, v155, v111, v19
	v_fma_f32 v26, v155, v115, v26
	v_fma_f32 v27, v155, v119, v27
	v_fma_f32 v60, v155, v123, v60
	v_fma_f32 v61, v155, v127, v61
	v_mov_b32_e32 v90, s46
	ds_read_b128 v[96:99], v90
	ds_read_b128 v[100:103], v90 offset:512
	ds_read_b128 v[104:107], v90 offset:1024
	ds_read_b128 v[108:111], v90 offset:1536
	ds_read_b128 v[112:115], v90 offset:2048
	ds_read_b128 v[116:119], v90 offset:2560
	ds_read_b128 v[120:123], v90 offset:3072
	ds_read_b128 v[124:127], v90 offset:3584
	s_add_i32 s46, s46, 16
	s_waitcnt lgkmcnt(8)
	s_waitcnt vmcnt(32)
	v_fma_f32 v10, v156, v208, v10
	v_fma_f32 v11, v156, v212, v11
	v_fma_f32 v18, v156, v216, v18
	v_fma_f32 v19, v156, v220, v19
	v_fma_f32 v26, v156, v224, v26
	v_fma_f32 v27, v156, v228, v27
	v_fma_f32 v60, v156, v232, v60
	v_fma_f32 v61, v156, v236, v61
	v_fma_f32 v10, v157, v209, v10
	v_fma_f32 v11, v157, v213, v11
	v_fma_f32 v18, v157, v217, v18
	v_fma_f32 v19, v157, v221, v19
	v_fma_f32 v26, v157, v225, v26
	v_fma_f32 v27, v157, v229, v27
	v_fma_f32 v60, v157, v233, v60
	v_fma_f32 v61, v157, v237, v61
	v_fma_f32 v10, v158, v210, v10
	v_fma_f32 v11, v158, v214, v11
	v_fma_f32 v18, v158, v218, v18
	v_fma_f32 v19, v158, v222, v19
	v_fma_f32 v26, v158, v226, v26
	v_fma_f32 v27, v158, v230, v27
	v_fma_f32 v60, v158, v234, v60
	v_fma_f32 v61, v158, v238, v61
	v_fma_f32 v10, v159, v211, v10
	v_fma_f32 v11, v159, v215, v11
	v_fma_f32 v18, v159, v219, v18
	v_fma_f32 v19, v159, v223, v19
	v_fma_f32 v26, v159, v227, v26
	v_fma_f32 v27, v159, v231, v27
	v_fma_f32 v60, v159, v235, v60
	v_fma_f32 v61, v159, v239, v61
	v_mov_b32_e32 v90, s46
	ds_read_b128 v[208:211], v90
	ds_read_b128 v[212:215], v90 offset:512
	ds_read_b128 v[216:219], v90 offset:1024
	ds_read_b128 v[220:223], v90 offset:1536
	ds_read_b128 v[224:227], v90 offset:2048
	ds_read_b128 v[228:231], v90 offset:2560
	ds_read_b128 v[232:235], v90 offset:3072
	ds_read_b128 v[236:239], v90 offset:3584
	s_add_i32 s46, s46, 16
	s_waitcnt lgkmcnt(8)
	s_waitcnt vmcnt(28)
	v_fma_f32 v10, v160, v96, v10
	v_fma_f32 v11, v160, v100, v11
	v_fma_f32 v18, v160, v104, v18
	v_fma_f32 v19, v160, v108, v19
	v_fma_f32 v26, v160, v112, v26
	v_fma_f32 v27, v160, v116, v27
	v_fma_f32 v60, v160, v120, v60
	v_fma_f32 v61, v160, v124, v61
	v_fma_f32 v10, v161, v97, v10
	v_fma_f32 v11, v161, v101, v11
	v_fma_f32 v18, v161, v105, v18
	v_fma_f32 v19, v161, v109, v19
	v_fma_f32 v26, v161, v113, v26
	v_fma_f32 v27, v161, v117, v27
	v_fma_f32 v60, v161, v121, v60
	v_fma_f32 v61, v161, v125, v61
	v_fma_f32 v10, v162, v98, v10
	v_fma_f32 v11, v162, v102, v11
	v_fma_f32 v18, v162, v106, v18
	v_fma_f32 v19, v162, v110, v19
	v_fma_f32 v26, v162, v114, v26
	v_fma_f32 v27, v162, v118, v27
	v_fma_f32 v60, v162, v122, v60
	v_fma_f32 v61, v162, v126, v61
	v_fma_f32 v10, v163, v99, v10
	v_fma_f32 v11, v163, v103, v11
	v_fma_f32 v18, v163, v107, v18
	v_fma_f32 v19, v163, v111, v19
	v_fma_f32 v26, v163, v115, v26
	v_fma_f32 v27, v163, v119, v27
	v_fma_f32 v60, v163, v123, v60
	v_fma_f32 v61, v163, v127, v61
	v_mov_b32_e32 v90, s46
	ds_read_b128 v[96:99], v90
	ds_read_b128 v[100:103], v90 offset:512
	ds_read_b128 v[104:107], v90 offset:1024
	ds_read_b128 v[108:111], v90 offset:1536
	ds_read_b128 v[112:115], v90 offset:2048
	ds_read_b128 v[116:119], v90 offset:2560
	ds_read_b128 v[120:123], v90 offset:3072
	ds_read_b128 v[124:127], v90 offset:3584
	s_add_i32 s46, s46, 16
	s_waitcnt lgkmcnt(8)
; DI int tidx() { int t = __builtin_amdgcn_workitem_id_x(); asm volatile("" : "+v"(t)); return t; }
; DI void phase_prologue_a(char* lds, const Params& p, int bid, int nb) {
;     ...
;       const int j = jb * 512 + tidx();
;       float a0 = 0.f, a1 = 0.f, a2 = 0.f, a3 = 0.f, a4 = 0.f, a5 = 0.f, a6 = 0.f, a7 = 0.f;
;       const float* w = p.w_ada + ((size_t)l * 1024 + kc * 128) * 6144 + j;
; #pragma unroll 4
;       for (int k = 0; k < 128; ++k) { const float wv = w[(size_t)k * 6144];
;         a0 += sl[k] * wv; a1 += sl[128 + k] * wv; a2 += sl[256 + k] * wv; a3 += sl[384 + k] * wv; a4 += sl[512 + k] * wv; a5 += sl[640 + k] * wv; a6 += sl[768 + k] * wv; a7 += sl[896 + k] * wv; }
	s_waitcnt vmcnt(24)
	v_fma_f32 v10, v164, v208, v10
	v_fma_f32 v11, v164, v212, v11
	v_fma_f32 v18, v164, v216, v18
	v_fma_f32 v19, v164, v220, v19
	v_fma_f32 v26, v164, v224, v26
	v_fma_f32 v27, v164, v228, v27
	v_fma_f32 v60, v164, v232, v60
	v_fma_f32 v61, v164, v236, v61
	v_fma_f32 v10, v165, v209, v10
	v_fma_f32 v11, v165, v213, v11
	v_fma_f32 v18, v165, v217, v18
	v_fma_f32 v19, v165, v221, v19
	v_fma_f32 v26, v165, v225, v26
	v_fma_f32 v27, v165, v229, v27
	v_fma_f32 v60, v165, v233, v60
	v_fma_f32 v61, v165, v237, v61
	v_fma_f32 v10, v166, v210, v10
	v_fma_f32 v11, v166, v214, v11
	v_fma_f32 v18, v166, v218, v18
	v_fma_f32 v19, v166, v222, v19
	v_fma_f32 v26, v166, v226, v26
	v_fma_f32 v27, v166, v230, v27
	v_fma_f32 v60, v166, v234, v60
	v_fma_f32 v61, v166, v238, v61
	v_fma_f32 v10, v167, v211, v10
	v_fma_f32 v11, v167, v215, v11
	v_fma_f32 v18, v167, v219, v18
	v_fma_f32 v19, v167, v223, v19
	v_fma_f32 v26, v167, v227, v26
	v_fma_f32 v27, v167, v231, v27
	v_fma_f32 v60, v167, v235, v60
	v_fma_f32 v61, v167, v239, v61
	v_mov_b32_e32 v90, s46
	ds_read_b128 v[208:211], v90
	ds_read_b128 v[212:215], v90 offset:512
	ds_read_b128 v[216:219], v90 offset:1024
	ds_read_b128 v[220:223], v90 offset:1536
	ds_read_b128 v[224:227], v90 offset:2048
	ds_read_b128 v[228:231], v90 offset:2560
	ds_read_b128 v[232:235], v90 offset:3072
	ds_read_b128 v[236:239], v90 offset:3584
	s_add_i32 s46, s46, 16
	s_waitcnt lgkmcnt(8)
	s_waitcnt vmcnt(20)
	v_fma_f32 v10, v168, v96, v10
	v_fma_f32 v11, v168, v100, v11
	v_fma_f32 v18, v168, v104, v18
	v_fma_f32 v19, v168, v108, v19
	v_fma_f32 v26, v168, v112, v26
	v_fma_f32 v27, v168, v116, v27
	v_fma_f32 v60, v168, v120, v60
	v_fma_f32 v61, v168, v124, v61
	v_fma_f32 v10, v169, v97, v10
	v_fma_f32 v11, v169, v101, v11
	v_fma_f32 v18, v169, v105, v18
	v_fma_f32 v19, v169, v109, v19
	v_fma_f32 v26, v169, v113, v26
	v_fma_f32 v27, v169, v117, v27
	v_fma_f32 v60, v169, v121, v60
	v_fma_f32 v61, v169, v125, v61
	v_fma_f32 v10, v170, v98, v10
	v_fma_f32 v11, v170, v102, v11
	v_fma_f32 v18, v170, v106, v18
	v_fma_f32 v19, v170, v110, v19
	v_fma_f32 v26, v170, v114, v26
	v_fma_f32 v27, v170, v118, v27
	v_fma_f32 v60, v170, v122, v60
	v_fma_f32 v61, v170, v126, v61
	v_fma_f32 v10, v171, v99, v10
	v_fma_f32 v11, v171, v103, v11
	v_fma_f32 v18, v171, v107, v18
	v_fma_f32 v19, v171, v111, v19
	v_fma_f32 v26, v171, v115, v26
	v_fma_f32 v27, v171, v119, v27
	v_fma_f32 v60, v171, v123, v60
	v_fma_f32 v61, v171, v127, v61
	v_mov_b32_e32 v90, s46
	ds_read_b128 v[96:99], v90
	ds_read_b128 v[100:103], v90 offset:512
	ds_read_b128 v[104:107], v90 offset:1024
	ds_read_b128 v[108:111], v90 offset:1536
	ds_read_b128 v[112:115], v90 offset:2048
	ds_read_b128 v[116:119], v90 offset:2560
	ds_read_b128 v[120:123], v90 offset:3072
	ds_read_b128 v[124:127], v90 offset:3584
	s_add_i32 s46, s46, 16
	s_waitcnt lgkmcnt(8)
	s_waitcnt vmcnt(16)
	v_fma_f32 v10, v172, v208, v10
	v_fma_f32 v11, v172, v212, v11
	v_fma_f32 v18, v172, v216, v18
	v_fma_f32 v19, v172, v220, v19
	v_fma_f32 v26, v172, v224, v26
	v_fma_f32 v27, v172, v228, v27
	v_fma_f32 v60, v172, v232, v60
	v_fma_f32 v61, v172, v236, v61
	v_fma_f32 v10, v173, v209, v10
	v_fma_f32 v11, v173, v213, v11
	v_fma_f32 v18, v173, v217, v18
	v_fma_f32 v19, v173, v221, v19
	v_fma_f32 v26, v173, v225, v26
	v_fma_f32 v27, v173, v229, v27
	v_fma_f32 v60, v173, v233, v60
	v_fma_f32 v61, v173, v237, v61
	v_fma_f32 v10, v174, v210, v10
	v_fma_f32 v11, v174, v214, v11
	v_fma_f32 v18, v174, v218, v18
	v_fma_f32 v19, v174, v222, v19
	v_fma_f32 v26, v174, v226, v26
	v_fma_f32 v27, v174, v230, v27
	v_fma_f32 v60, v174, v234, v60
	v_fma_f32 v61, v174, v238, v61
	v_fma_f32 v10, v175, v211, v10
	v_fma_f32 v11, v175, v215, v11
	v_fma_f32 v18, v175, v219, v18
	v_fma_f32 v19, v175, v223, v19
	v_fma_f32 v26, v175, v227, v26
	v_fma_f32 v27, v175, v231, v27
	v_fma_f32 v60, v175, v235, v60
	v_fma_f32 v61, v175, v239, v61
	v_mov_b32_e32 v90, s46
	ds_read_b128 v[208:211], v90
	ds_read_b128 v[212:215], v90 offset:512
	ds_read_b128 v[216:219], v90 offset:1024
	ds_read_b128 v[220:223], v90 offset:1536
	ds_read_b128 v[224:227], v90 offset:2048
	ds_read_b128 v[228:231], v90 offset:2560
	ds_read_b128 v[232:235], v90 offset:3072
	ds_read_b128 v[236:239], v90 offset:3584
	s_add_i32 s46, s46, 16
	s_waitcnt lgkmcnt(8)
	s_waitcnt vmcnt(12)
	v_fma_f32 v10, v176, v96, v10
	v_fma_f32 v11, v176, v100, v11
	v_fma_f32 v18, v176, v104, v18
	v_fma_f32 v19, v176, v108, v19
	v_fma_f32 v26, v176, v112, v26
	v_fma_f32 v27, v176, v116, v27
	v_fma_f32 v60, v176, v120, v60
	v_fma_f32 v61, v176, v124, v61
	v_fma_f32 v10, v177, v97, v10
	v_fma_f32 v11, v177, v101, v11
	v_fma_f32 v18, v177, v105, v18
	v_fma_f32 v19, v177, v109, v19
	v_fma_f32 v26, v177, v113, v26
	v_fma_f32 v27, v177, v117, v27
	v_fma_f32 v60, v177, v121, v60
	v_fma_f32 v61, v177, v125, v61
	v_fma_f32 v10, v178, v98, v10
	v_fma_f32 v11, v178, v102, v11
	v_fma_f32 v18, v178, v106, v18
	v_fma_f32 v19, v178, v110, v19
	v_fma_f32 v26, v178, v114, v26
	v_fma_f32 v27, v178, v118, v27
	v_fma_f32 v60, v178, v122, v60
	v_fma_f32 v61, v178, v126, v61
	v_fma_f32 v10, v179, v99, v10
	v_fma_f32 v11, v179, v103, v11
	v_fma_f32 v18, v179, v107, v18
	v_fma_f32 v19, v179, v111, v19
	v_fma_f32 v26, v179, v115, v26
	v_fma_f32 v27, v179, v119, v27
	v_fma_f32 v60, v179, v123, v60
	v_fma_f32 v61, v179, v127, v61
	v_mov_b32_e32 v90, s46
	ds_read_b128 v[96:99], v90
	ds_read_b128 v[100:103], v90 offset:512
	ds_read_b128 v[104:107], v90 offset:1024
	ds_read_b128 v[108:111], v90 offset:1536
	ds_read_b128 v[112:115], v90 offset:2048
	ds_read_b128 v[116:119], v90 offset:2560
	ds_read_b128 v[120:123], v90 offset:3072
	ds_read_b128 v[124:127], v90 offset:3584
	s_add_i32 s46, s46, 16
	s_waitcnt lgkmcnt(8)
; DI int tidx() { int t = __builtin_amdgcn_workitem_id_x(); asm volatile("" : "+v"(t)); return t; }
; DI void phase_prologue_a(char* lds, const Params& p, int bid, int nb) {
;     ...
;       const int j = jb * 512 + tidx();
;       float a0 = 0.f, a1 = 0.f, a2 = 0.f, a3 = 0.f, a4 = 0.f, a5 = 0.f, a6 = 0.f, a7 = 0.f;
;       const float* w = p.w_ada + ((size_t)l * 1024 + kc * 128) * 6144 + j;
; #pragma unroll 4
;       for (int k = 0; k < 128; ++k) { const float wv = w[(size_t)k * 6144];
;         a0 += sl[k] * wv; a1 += sl[128 + k] * wv; a2 += sl[256 + k] * wv; a3 += sl[384 + k] * wv; a4 += sl[512 + k] * wv; a5 += sl[640 + k] * wv; a6 += sl[768 + k] * wv; a7 += sl[896 + k] * wv; }
;       float* d = p.modp + ((size_t)(kc * 2 + l) * 8) * 6144 + j;
;       d[0] = a0; d[6144] = a1; d[2 * 6144] = a2; d[3 * 6144] = a3; d[4 * 6144] = a4; d[5 * 6144] = a5; d[6 * 6144] = a6; d[7 * 6144] = a7;
;       __syncthreads();
	s_waitcnt vmcnt(8)
	v_fma_f32 v10, v180, v208, v10
	v_fma_f32 v11, v180, v212, v11
	v_fma_f32 v18, v180, v216, v18
	v_fma_f32 v19, v180, v220, v19
	v_fma_f32 v26, v180, v224, v26
	v_fma_f32 v27, v180, v228, v27
	v_fma_f32 v60, v180, v232, v60
	v_fma_f32 v61, v180, v236, v61
	v_fma_f32 v10, v181, v209, v10
	v_fma_f32 v11, v181, v213, v11
	v_fma_f32 v18, v181, v217, v18
	v_fma_f32 v19, v181, v221, v19
	v_fma_f32 v26, v181, v225, v26
	v_fma_f32 v27, v181, v229, v27
	v_fma_f32 v60, v181, v233, v60
	v_fma_f32 v61, v181, v237, v61
	v_fma_f32 v10, v182, v210, v10
	v_fma_f32 v11, v182, v214, v11
	v_fma_f32 v18, v182, v218, v18
	v_fma_f32 v19, v182, v222, v19
	v_fma_f32 v26, v182, v226, v26
	v_fma_f32 v27, v182, v230, v27
	v_fma_f32 v60, v182, v234, v60
	v_fma_f32 v61, v182, v238, v61
	v_fma_f32 v10, v183, v211, v10
	v_fma_f32 v11, v183, v215, v11
	v_fma_f32 v18, v183, v219, v18
	v_fma_f32 v19, v183, v223, v19
	v_fma_f32 v26, v183, v227, v26
	v_fma_f32 v27, v183, v231, v27
	v_fma_f32 v60, v183, v235, v60
	v_fma_f32 v61, v183, v239, v61
	v_mov_b32_e32 v90, s46
	ds_read_b128 v[208:211], v90
	ds_read_b128 v[212:215], v90 offset:512
	ds_read_b128 v[216:219], v90 offset:1024
	ds_read_b128 v[220:223], v90 offset:1536
	ds_read_b128 v[224:227], v90 offset:2048
	ds_read_b128 v[228:231], v90 offset:2560
	ds_read_b128 v[232:235], v90 offset:3072
	ds_read_b128 v[236:239], v90 offset:3584
	s_add_i32 s46, s46, 16
	s_waitcnt lgkmcnt(8)
	s_waitcnt vmcnt(4)
	v_fma_f32 v10, v184, v96, v10
	v_fma_f32 v11, v184, v100, v11
	v_fma_f32 v18, v184, v104, v18
	v_fma_f32 v19, v184, v108, v19
	v_fma_f32 v26, v184, v112, v26
	v_fma_f32 v27, v184, v116, v27
	v_fma_f32 v60, v184, v120, v60
	v_fma_f32 v61, v184, v124, v61
	v_fma_f32 v10, v185, v97, v10
	v_fma_f32 v11, v185, v101, v11
	v_fma_f32 v18, v185, v105, v18
	v_fma_f32 v19, v185, v109, v19
	v_fma_f32 v26, v185, v113, v26
	v_fma_f32 v27, v185, v117, v27
	v_fma_f32 v60, v185, v121, v60
	v_fma_f32 v61, v185, v125, v61
	v_fma_f32 v10, v186, v98, v10
	v_fma_f32 v11, v186, v102, v11
	v_fma_f32 v18, v186, v106, v18
	v_fma_f32 v19, v186, v110, v19
	v_fma_f32 v26, v186, v114, v26
	v_fma_f32 v27, v186, v118, v27
	v_fma_f32 v60, v186, v122, v60
	v_fma_f32 v61, v186, v126, v61
	v_fma_f32 v10, v187, v99, v10
	v_fma_f32 v11, v187, v103, v11
	v_fma_f32 v18, v187, v107, v18
	v_fma_f32 v19, v187, v111, v19
	v_fma_f32 v26, v187, v115, v26
	v_fma_f32 v27, v187, v119, v27
	v_fma_f32 v60, v187, v123, v60
	v_fma_f32 v61, v187, v127, v61
	s_waitcnt lgkmcnt(0)
	s_waitcnt vmcnt(0)
	v_fma_f32 v10, v188, v208, v10
	v_fma_f32 v11, v188, v212, v11
	v_fma_f32 v18, v188, v216, v18
	v_fma_f32 v19, v188, v220, v19
	v_fma_f32 v26, v188, v224, v26
	v_fma_f32 v27, v188, v228, v27
	v_fma_f32 v60, v188, v232, v60
	v_fma_f32 v61, v188, v236, v61
	v_fma_f32 v10, v189, v209, v10
	v_fma_f32 v11, v189, v213, v11
	v_fma_f32 v18, v189, v217, v18
	v_fma_f32 v19, v189, v221, v19
	v_fma_f32 v26, v189, v225, v26
	v_fma_f32 v27, v189, v229, v27
	v_fma_f32 v60, v189, v233, v60
	v_fma_f32 v61, v189, v237, v61
	v_fma_f32 v10, v190, v210, v10
	v_fma_f32 v11, v190, v214, v11
	v_fma_f32 v18, v190, v218, v18
	v_fma_f32 v19, v190, v222, v19
	v_fma_f32 v26, v190, v226, v26
	v_fma_f32 v27, v190, v230, v27
	v_fma_f32 v60, v190, v234, v60
	v_fma_f32 v61, v190, v238, v61
	v_fma_f32 v10, v191, v211, v10
	v_fma_f32 v11, v191, v215, v11
	v_fma_f32 v18, v191, v219, v18
	v_fma_f32 v19, v191, v223, v19
	v_fma_f32 v26, v191, v227, v26
	v_fma_f32 v27, v191, v231, v27
	v_fma_f32 v60, v191, v235, v60
	v_fma_f32 v61, v191, v239, v61
	s_cmp_eq_u32 s4, 0x300000
	s_cbranch_scc0 .Lada_batch
	s_mov_b32 s47, 0x12000
	s_lshl_b32 s4, s8, 4
	s_and_b64 s[0:1], s[0:1], exec
	s_cselect_b32 s0, 8, 0
	s_or_b32 s0, s0, s4
	v_readlane_b32 s16, v252, 17
	s_mulk_i32 s0, 0x6000
	v_readlane_b32 s22, v252, 23
	v_readlane_b32 s23, v252, 24
	s_add_u32 s0, s22, s0
	s_addc_u32 s1, s23, 0
	v_lshl_add_u64 v[2:3], v[56:57], 2, s[0:1]
	v_add_co_u32_e32 v4, vcc, 0x6000, v2
	global_store_dword v[2:3], v10, off
	s_nop 0
	v_addc_co_u32_e32 v5, vcc, 0, v3, vcc
	global_store_dword v[4:5], v11, off
	v_add_co_u32_e32 v4, vcc, 0xc000, v2
	v_readlane_b32 s17, v252, 18
	s_nop 0
	v_addc_co_u32_e32 v5, vcc, 0, v3, vcc
	global_store_dword v[4:5], v18, off
	v_add_co_u32_e32 v4, vcc, 0x12000, v2
	v_readlane_b32 s18, v252, 19
	s_nop 0
	v_addc_co_u32_e32 v5, vcc, 0, v3, vcc
	global_store_dword v[4:5], v19, off
	v_add_co_u32_e32 v4, vcc, 0x18000, v2
	v_readlane_b32 s19, v252, 20
	s_nop 0
	v_addc_co_u32_e32 v5, vcc, 0, v3, vcc
	global_store_dword v[4:5], v26, off
	v_add_co_u32_e32 v4, vcc, 0x1e000, v2
	v_readlane_b32 s20, v252, 21
	s_nop 0
	v_addc_co_u32_e32 v5, vcc, 0, v3, vcc
	global_store_dword v[4:5], v27, off
	v_add_co_u32_e32 v4, vcc, 0x24000, v2
	v_readlane_b32 s21, v252, 22
	s_nop 0
	v_addc_co_u32_e32 v5, vcc, 0, v3, vcc
	v_add_co_u32_e32 v2, vcc, 0x2a000, v2
	v_readlane_b32 s24, v252, 25
	s_nop 0
	v_addc_co_u32_e32 v3, vcc, 0, v3, vcc
	v_readlane_b32 s25, v252, 26
	v_readlane_b32 s26, v252, 27
	v_readlane_b32 s27, v252, 28
	v_readlane_b32 s28, v252, 29
	v_readlane_b32 s29, v252, 30
	v_readlane_b32 s30, v252, 31
	v_readlane_b32 s31, v252, 32
	global_store_dword v[4:5], v60, off
	global_store_dword v[2:3], v61, off
	s_barrier
